# v19 with flatter w_in_b rank classes 10/9/9/8/8/7/7/6
# speedup vs baseline: 1.0026x; 1.0026x over previous
; __global__ void __launch_bounds__(NTHREADS, 2) mk_fwd(Params P) {
;     ...
;     if (IN(5)) {
;         transpose_convert(lds, P.w_in_b, WINB, 2048, 8192, G, bid);
.LBB0_416:
	s_cmp_lt_i32 s42, 6
	s_cselect_b64 s[0:1], -1, 0
	s_cmp_gt_i32 s43, 5
	s_setprio 0
	s_cselect_b64 s[4:5], -1, 0
	s_and_b64 s[0:1], s[0:1], s[4:5]
	s_andn2_b64 vcc, exec, s[0:1]
	s_cbranch_vccnz .LBB0_448
	v_and_b32_e32 v20, 15, v164
	v_mov_b32_e32 v46, 0x20008
	ds_read_b32 v48, v46
	s_waitcnt lgkmcnt(0)
	v_readfirstlane_b32 s99, v48
	s_and_b32 s99, s99, 0xff
	s_lshr_b32 s3, s99, 5
	s_and_b32 s4, s99, 31
	s_mov_b32 s100, 10
	s_mov_b32 s5, 0
	s_cmp_lt_u32 s3, 1
	s_cbranch_scc1 .Lrk5_done
	s_mov_b32 s100, 9
	s_movk_i32 s5, 320
	s_cmp_lt_u32 s3, 2
	s_cbranch_scc1 .Lrk5_done
	s_mov_b32 s100, 9
	s_movk_i32 s5, 608
	s_cmp_lt_u32 s3, 3
	s_cbranch_scc1 .Lrk5_done
	s_mov_b32 s100, 8
	s_movk_i32 s5, 896
	s_cmp_lt_u32 s3, 4
	s_cbranch_scc1 .Lrk5_done
	s_mov_b32 s100, 8
	s_movk_i32 s5, 1152
	s_cmp_lt_u32 s3, 5
	s_cbranch_scc1 .Lrk5_done
	s_mov_b32 s100, 7
	s_movk_i32 s5, 1408
	s_cmp_lt_u32 s3, 6
	s_cbranch_scc1 .Lrk5_done
	s_mov_b32 s100, 7
	s_movk_i32 s5, 1632
	s_cmp_lt_u32 s3, 7
	s_cbranch_scc1 .Lrk5_done
	s_mov_b32 s100, 6
	s_movk_i32 s5, 1856
